# speedup vs baseline: 1.0082x; 1.0041x over previous
; template <class Epi, class Sched, bool ALIGN_EPI = false, bool SP2 = false>
; __device__ __forceinline__ void gemm_phase(PG8_LAS unsigned char* lds, const Gemm g, const Sched& S, const Epi& E) {
;     ...
;         const bool has_next = S.next(ui + 1, nxt);
;         const char* nA = has_next ? (const char*)g.A + (size_t)nxt.pm * tstep + (size_t)nxt.k0 * 2 : cA; const char* nB = has_next ? (const char*)g.Bt + (size_t)nxt.pn * tstep + (size_t)nxt.k0 * 2 : cB;
;         const int nt = cur.nt;
;         for (int t = 0; t < nt; t += 2) {
;     ...
;         for (int a = 0; a < 2; ++a)
; #pragma unroll
;             for (int b = 0; b < 2; ++b)
; #pragma unroll
;                 for (int m = 0; m < 4; ++m)
; #pragma unroll
;                     for (int n = 0; n < 2; ++n) acc[a][b][m][n] = (f32x4){0.f, 0.f, 0.f, 0.f};
.LBB0_69:
	s_ashr_i32 s29, s28, 31
	s_lshl_b64 s[30:31], s[28:29], 20
	s_add_u32 s30, s33, s30
	s_addc_u32 s31, s35, s31
	s_and_b64 s[44:45], s[4:5], exec
	s_cselect_b32 s29, s31, s49
	s_cselect_b32 s65, s30, s48
	s_ashr_i32 s27, s26, 31
	s_lshl_b64 s[44:45], s[26:27], 20
	s_add_u32 s44, s12, s44
	s_addc_u32 s45, s13, s45
	s_and_b64 s[52:53], s[4:5], exec
	s_cselect_b32 s27, s45, s51
	s_cselect_b32 s67, s44, s50
	s_add_u32 s48, s48, 0x80080
	s_addc_u32 s49, s49, 0
	s_add_u32 s68, s50, 0x100
	v_mov_b32_e32 v2, 0
	s_addc_u32 s69, s51, 0
	s_mov_b32 s70, -2
	v_mov_b32_e32 v3, v2
	v_mov_b64_e32 v[4:5], 0
	v_mov_b64_e32 v[10:11], 0
	v_mov_b64_e32 v[12:13], 0
	v_mov_b64_e32 v[18:19], 0
	v_mov_b64_e32 v[20:21], 0
	v_mov_b64_e32 v[26:27], 0
	v_mov_b64_e32 v[28:29], 0
	v_mov_b64_e32 v[34:35], 0
	v_mov_b64_e32 v[36:37], 0
	v_mov_b64_e32 v[42:43], 0
	v_mov_b64_e32 v[44:45], 0
	v_mov_b64_e32 v[50:51], 0
	v_mov_b64_e32 v[52:53], 0
	v_mov_b64_e32 v[58:59], 0
	v_mov_b64_e32 v[60:61], 0
	v_mov_b64_e32 v[6:7], 0
	v_mov_b64_e32 v[8:9], 0
	v_mov_b64_e32 v[14:15], 0
	v_mov_b64_e32 v[16:17], 0
	v_mov_b64_e32 v[22:23], 0
	v_mov_b64_e32 v[24:25], 0
	v_mov_b64_e32 v[30:31], 0
	v_mov_b64_e32 v[32:33], 0
	v_mov_b64_e32 v[38:39], 0
	v_mov_b64_e32 v[40:41], 0
	v_mov_b64_e32 v[46:47], 0
	v_mov_b64_e32 v[48:49], 0
	v_mov_b64_e32 v[54:55], 0
	v_mov_b64_e32 v[56:57], 0
	v_mov_b64_e32 v[62:63], 0
	v_mov_b64_e32 v[64:65], 0
	v_mov_b64_e32 v[66:67], 0
	v_mov_b64_e32 v[68:69], 0
	v_mov_b64_e32 v[74:75], 0
	v_mov_b64_e32 v[76:77], 0
	v_mov_b64_e32 v[82:83], 0
	v_mov_b64_e32 v[84:85], 0
	v_mov_b64_e32 v[90:91], 0
	v_mov_b64_e32 v[92:93], 0
	v_mov_b64_e32 v[98:99], 0
	v_mov_b64_e32 v[100:101], 0
	v_mov_b64_e32 v[106:107], 0
	v_mov_b64_e32 v[108:109], 0
	v_mov_b64_e32 v[114:115], 0
	v_mov_b64_e32 v[116:117], 0
	v_mov_b64_e32 v[122:123], 0
	v_mov_b64_e32 v[124:125], 0
	v_mov_b64_e32 v[70:71], 0
	v_mov_b64_e32 v[72:73], 0
	v_mov_b64_e32 v[78:79], 0
	v_mov_b64_e32 v[80:81], 0
	v_mov_b64_e32 v[86:87], 0
	v_mov_b64_e32 v[88:89], 0
	v_mov_b64_e32 v[94:95], 0
	v_mov_b64_e32 v[96:97], 0
	v_mov_b64_e32 v[102:103], 0
	v_mov_b64_e32 v[104:105], 0
	v_mov_b64_e32 v[110:111], 0
	v_mov_b64_e32 v[112:113], 0
	v_mov_b64_e32 v[118:119], 0
	v_mov_b64_e32 v[120:121], 0
	v_mov_b64_e32 v[126:127], 0
	v_mov_b64_e32 v[128:129], 0

; template <class Epi, class Sched, bool ALIGN_EPI = false, bool SP2 = false>
; __device__ __forceinline__ void gemm_phase(PG8_LAS unsigned char* lds, const Gemm g, const Sched& S, const Epi& E) {
;     ...
;         const int nt = cur.nt;
;         for (int t = 0; t < nt; t += 2) {
;             const bool last = (t == nt - 2);
;             const char* a1 = cA + (size_t)(t + 1) * kstep;
;             const char* a2 = last ? nA : cA + (size_t)(t + 2) * kstep; const char* b2 = last ? nB : cB + (size_t)(t + 2) * kstep;
;     ...
;         for (int a = 0; a < 2; ++a)
; #pragma unroll
;             for (int b = 0; b < 2; ++b)
; #pragma unroll
;                 for (int m = 0; m < 4; ++m)
; #pragma unroll
;                     for (int n = 0; n < 2; ++n) acc[a][b][m][n] = (f32x4){0.f, 0.f, 0.f, 0.f};
.LBB0_178:
	s_add_i32 s76, s75, -2
	s_add_u32 s8, s8, 0x158080
	s_addc_u32 s9, s9, 0
	s_add_u32 s77, s50, 0x100
	v_mov_b32_e32 v2, 0
	s_addc_u32 s78, s51, 0
	s_mov_b32 s50, 0
	v_mov_b32_e32 v3, v2
	v_mov_b64_e32 v[4:5], 0
	v_mov_b64_e32 v[6:7], 0
	v_mov_b64_e32 v[8:9], 0
	v_mov_b64_e32 v[14:15], 0
	v_mov_b64_e32 v[16:17], 0
	v_mov_b64_e32 v[22:23], 0
	v_mov_b64_e32 v[24:25], 0
	v_mov_b64_e32 v[30:31], 0
	v_mov_b64_e32 v[32:33], 0
	v_mov_b64_e32 v[38:39], 0
	v_mov_b64_e32 v[40:41], 0
	v_mov_b64_e32 v[46:47], 0
	v_mov_b64_e32 v[48:49], 0
	v_mov_b64_e32 v[54:55], 0
	v_mov_b64_e32 v[56:57], 0
	v_mov_b64_e32 v[10:11], 0
	v_mov_b64_e32 v[12:13], 0
	v_mov_b64_e32 v[18:19], 0
	v_mov_b64_e32 v[20:21], 0
	v_mov_b64_e32 v[26:27], 0
	v_mov_b64_e32 v[28:29], 0
	v_mov_b64_e32 v[34:35], 0
	v_mov_b64_e32 v[36:37], 0
	v_mov_b64_e32 v[42:43], 0
	v_mov_b64_e32 v[44:45], 0
	v_mov_b64_e32 v[50:51], 0
	v_mov_b64_e32 v[52:53], 0
	v_mov_b64_e32 v[58:59], 0
	v_mov_b64_e32 v[60:61], 0
	v_mov_b64_e32 v[62:63], 0
	v_mov_b64_e32 v[64:65], 0
	v_mov_b64_e32 v[66:67], 0
	v_mov_b64_e32 v[68:69], 0
	v_mov_b64_e32 v[70:71], 0
	v_mov_b64_e32 v[72:73], 0
	v_mov_b64_e32 v[78:79], 0
	v_mov_b64_e32 v[80:81], 0
	v_mov_b64_e32 v[86:87], 0
	v_mov_b64_e32 v[88:89], 0
	v_mov_b64_e32 v[94:95], 0
	v_mov_b64_e32 v[96:97], 0
	v_mov_b64_e32 v[102:103], 0
	v_mov_b64_e32 v[104:105], 0
	v_mov_b64_e32 v[110:111], 0
	v_mov_b64_e32 v[112:113], 0
	v_mov_b64_e32 v[118:119], 0
	v_mov_b64_e32 v[120:121], 0
	v_mov_b64_e32 v[74:75], 0
	v_mov_b64_e32 v[76:77], 0
	v_mov_b64_e32 v[82:83], 0
	v_mov_b64_e32 v[84:85], 0
	v_mov_b64_e32 v[90:91], 0
	v_mov_b64_e32 v[92:93], 0
	v_mov_b64_e32 v[98:99], 0
	v_mov_b64_e32 v[100:101], 0
	v_mov_b64_e32 v[106:107], 0
	v_mov_b64_e32 v[108:109], 0
	v_mov_b64_e32 v[114:115], 0
	v_mov_b64_e32 v[116:117], 0
	v_mov_b64_e32 v[122:123], 0
	v_mov_b64_e32 v[124:125], 0
	v_mov_b64_e32 v[126:127], 0
	v_mov_b64_e32 v[128:129], 0

; template <class Epi, class Sched, bool ALIGN_EPI = false, bool SP2 = false>
; __device__ __forceinline__ void gemm_phase(PG8_LAS unsigned char* lds, const Gemm g, const Sched& S, const Epi& E) {
;     ...
;         const bool has_next = S.next(ui + 1, nxt);
;         const char* nA = has_next ? (const char*)g.A + (size_t)nxt.pm * tstep + (size_t)nxt.k0 * 2 : cA; const char* nB = has_next ? (const char*)g.Bt + (size_t)nxt.pn * tstep + (size_t)nxt.k0 * 2 : cB;
;         const int nt = cur.nt;
;         for (int t = 0; t < nt; t += 2) {
;     ...
;         for (int a = 0; a < 2; ++a)
; #pragma unroll
;             for (int b = 0; b < 2; ++b)
; #pragma unroll
;                 for (int m = 0; m < 4; ++m)
; #pragma unroll
;                     for (int n = 0; n < 2; ++n) acc[a][b][m][n] = (f32x4){0.f, 0.f, 0.f, 0.f};
.LBB0_393:
	s_ashr_i32 s27, s26, 31
	s_lshl_b64 s[28:29], s[26:27], 20
	s_add_u32 s28, s33, s28
	s_addc_u32 s29, s35, s29
	s_and_b64 s[30:31], s[4:5], exec
	s_cselect_b32 s7, s29, s47
	s_cselect_b32 s27, s28, s46
	s_ashr_i32 s25, s24, 31
	s_lshl_b64 s[30:31], s[24:25], 20
	s_add_u32 s30, s37, s30
	s_addc_u32 s31, s42, s31
	s_and_b64 s[50:51], s[4:5], exec
	s_cselect_b32 s25, s31, s49
	s_cselect_b32 s45, s30, s48
	s_add_u32 s46, s46, 0x80080
	s_addc_u32 s47, s47, 0
	s_add_u32 s68, s48, 0x100
	v_mov_b32_e32 v2, 0
	s_addc_u32 s69, s49, 0
	s_mov_b32 s70, -2
	v_mov_b32_e32 v3, v2
	v_mov_b64_e32 v[4:5], 0
	v_mov_b64_e32 v[6:7], 0
	v_mov_b64_e32 v[8:9], 0
	v_mov_b64_e32 v[14:15], 0
	v_mov_b64_e32 v[16:17], 0
	v_mov_b64_e32 v[22:23], 0
	v_mov_b64_e32 v[24:25], 0
	v_mov_b64_e32 v[30:31], 0
	v_mov_b64_e32 v[32:33], 0
	v_mov_b64_e32 v[38:39], 0
	v_mov_b64_e32 v[40:41], 0
	v_mov_b64_e32 v[46:47], 0
	v_mov_b64_e32 v[48:49], 0
	v_mov_b64_e32 v[54:55], 0
	v_mov_b64_e32 v[56:57], 0
	v_mov_b64_e32 v[10:11], 0
	v_mov_b64_e32 v[12:13], 0
	v_mov_b64_e32 v[18:19], 0
	v_mov_b64_e32 v[20:21], 0
	v_mov_b64_e32 v[26:27], 0
	v_mov_b64_e32 v[28:29], 0
	v_mov_b64_e32 v[34:35], 0
	v_mov_b64_e32 v[36:37], 0
	v_mov_b64_e32 v[42:43], 0
	v_mov_b64_e32 v[44:45], 0
	v_mov_b64_e32 v[50:51], 0
	v_mov_b64_e32 v[52:53], 0
	v_mov_b64_e32 v[58:59], 0
	v_mov_b64_e32 v[60:61], 0
	v_mov_b64_e32 v[62:63], 0
	v_mov_b64_e32 v[64:65], 0
	v_mov_b64_e32 v[66:67], 0
	v_mov_b64_e32 v[68:69], 0
	v_mov_b64_e32 v[70:71], 0
	v_mov_b64_e32 v[72:73], 0
	v_mov_b64_e32 v[78:79], 0
	v_mov_b64_e32 v[80:81], 0
	v_mov_b64_e32 v[86:87], 0
	v_mov_b64_e32 v[88:89], 0
	v_mov_b64_e32 v[94:95], 0
	v_mov_b64_e32 v[96:97], 0
	v_mov_b64_e32 v[102:103], 0
	v_mov_b64_e32 v[104:105], 0
	v_mov_b64_e32 v[110:111], 0
	v_mov_b64_e32 v[112:113], 0
	v_mov_b64_e32 v[118:119], 0
	v_mov_b64_e32 v[120:121], 0
	v_mov_b64_e32 v[74:75], 0
	v_mov_b64_e32 v[76:77], 0
	v_mov_b64_e32 v[82:83], 0
	v_mov_b64_e32 v[84:85], 0
	v_mov_b64_e32 v[90:91], 0
	v_mov_b64_e32 v[92:93], 0
	v_mov_b64_e32 v[98:99], 0
	v_mov_b64_e32 v[100:101], 0
	v_mov_b64_e32 v[106:107], 0
	v_mov_b64_e32 v[108:109], 0
	v_mov_b64_e32 v[114:115], 0
	v_mov_b64_e32 v[116:117], 0
	v_mov_b64_e32 v[122:123], 0
	v_mov_b64_e32 v[124:125], 0
	v_mov_b64_e32 v[126:127], 0
	v_mov_b64_e32 v[128:129], 0

; template <class Epi, class Sched, bool ALIGN_EPI = false, bool SP2 = false>
; __device__ __forceinline__ void gemm_phase(PG8_LAS unsigned char* lds, const Gemm g, const Sched& S, const Epi& E) {
;     ...
;         const int nt = cur.nt;
;         for (int t = 0; t < nt; t += 2) {
;             const bool last = (t == nt - 2);
;             const char* a1 = cA + (size_t)(t + 1) * kstep;
;             const char* a2 = last ? nA : cA + (size_t)(t + 2) * kstep; const char* b2 = last ? nB : cB + (size_t)(t + 2) * kstep;
;     ...
;         for (int a = 0; a < 2; ++a)
; #pragma unroll
;             for (int b = 0; b < 2; ++b)
; #pragma unroll
;                 for (int m = 0; m < 4; ++m)
; #pragma unroll
;                     for (int n = 0; n < 2; ++n) acc[a][b][m][n] = (f32x4){0.f, 0.f, 0.f, 0.f};
.LBB0_676:
	s_add_i32 s73, s72, -2
	s_add_u32 s6, s50, 0x80
	s_addc_u32 s7, s51, 0
	s_add_u32 s50, s48, 0x100
	v_mov_b32_e32 v2, 0
	s_addc_u32 s51, s49, 0
	s_mov_b32 s48, 0
	v_mov_b32_e32 v3, v2
	v_mov_b64_e32 v[4:5], 0
	v_mov_b64_e32 v[6:7], 0
	v_mov_b64_e32 v[8:9], 0
	v_mov_b64_e32 v[10:11], 0
	v_mov_b64_e32 v[12:13], 0
	v_mov_b64_e32 v[14:15], 0
	v_mov_b64_e32 v[16:17], 0
	v_mov_b64_e32 v[18:19], 0
	v_mov_b64_e32 v[20:21], 0
	v_mov_b64_e32 v[22:23], 0
	v_mov_b64_e32 v[24:25], 0
	v_mov_b64_e32 v[26:27], 0
	v_mov_b64_e32 v[28:29], 0
	v_mov_b64_e32 v[30:31], 0
	v_mov_b64_e32 v[32:33], 0
	v_mov_b64_e32 v[66:67], 0
	v_mov_b64_e32 v[68:69], 0
	v_mov_b64_e32 v[70:71], 0
	v_mov_b64_e32 v[72:73], 0
	v_mov_b64_e32 v[76:77], 0
	v_mov_b64_e32 v[78:79], 0
	v_mov_b64_e32 v[80:81], 0
	v_mov_b64_e32 v[82:83], 0
	v_mov_b64_e32 v[84:85], 0
	v_mov_b64_e32 v[86:87], 0
	v_mov_b64_e32 v[88:89], 0
	v_mov_b64_e32 v[90:91], 0
	v_mov_b64_e32 v[92:93], 0
	v_mov_b64_e32 v[94:95], 0
	v_mov_b64_e32 v[96:97], 0
	v_mov_b64_e32 v[98:99], 0
	v_mov_b64_e32 v[34:35], 0
	v_mov_b64_e32 v[36:37], 0
	v_mov_b64_e32 v[38:39], 0
	v_mov_b64_e32 v[40:41], 0
	v_mov_b64_e32 v[42:43], 0
	v_mov_b64_e32 v[44:45], 0
	v_mov_b64_e32 v[46:47], 0
	v_mov_b64_e32 v[48:49], 0
	v_mov_b64_e32 v[50:51], 0
	v_mov_b64_e32 v[52:53], 0
	v_mov_b64_e32 v[54:55], 0
	v_mov_b64_e32 v[56:57], 0
	v_mov_b64_e32 v[58:59], 0
	v_mov_b64_e32 v[60:61], 0
	v_mov_b64_e32 v[62:63], 0
	v_mov_b64_e32 v[64:65], 0
	v_mov_b64_e32 v[100:101], 0
	v_mov_b64_e32 v[102:103], 0
	v_mov_b64_e32 v[104:105], 0
	v_mov_b64_e32 v[106:107], 0
	v_mov_b64_e32 v[108:109], 0
	v_mov_b64_e32 v[110:111], 0
	v_mov_b64_e32 v[112:113], 0
	v_mov_b64_e32 v[114:115], 0
	v_mov_b64_e32 v[116:117], 0
	v_mov_b64_e32 v[118:119], 0
	v_mov_b64_e32 v[120:121], 0
	v_mov_b64_e32 v[122:123], 0
	v_mov_b64_e32 v[124:125], 0
	v_mov_b64_e32 v[126:127], 0
	v_mov_b64_e32 v[128:129], 0
	v_mov_b64_e32 v[130:131], 0

; template <class Epi, class Sched, bool ALIGN_EPI = false, bool SP2 = false>
; __device__ __forceinline__ void gemm_phase(PG8_LAS unsigned char* lds, const Gemm g, const Sched& S, const Epi& E) {
;     ...
;         const int nt = cur.nt;
;         for (int t = 0; t < nt; t += 2) {
;             const bool last = (t == nt - 2);
;             const char* a1 = cA + (size_t)(t + 1) * kstep;
;             const char* a2 = last ? nA : cA + (size_t)(t + 2) * kstep; const char* b2 = last ? nB : cB + (size_t)(t + 2) * kstep;
;     ...
;         for (int a = 0; a < 2; ++a)
; #pragma unroll
;             for (int b = 0; b < 2; ++b)
; #pragma unroll
;                 for (int m = 0; m < 4; ++m)
; #pragma unroll
;                     for (int n = 0; n < 2; ++n) acc[a][b][m][n] = (f32x4){0.f, 0.f, 0.f, 0.f};
.LBB0_1012:
	s_add_i32 s9, s78, -2
	s_add_u32 s56, s56, 0x80080
	s_addc_u32 s57, s57, 0
	s_add_u32 s47, s58, 0x100
	v_mov_b32_e32 v2, 0
	s_addc_u32 s51, s59, 0
	s_mov_b32 s55, 0
	v_mov_b32_e32 v3, v2
	v_mov_b64_e32 v[4:5], 0
	v_mov_b64_e32 v[6:7], 0
	v_mov_b64_e32 v[8:9], 0
	v_mov_b64_e32 v[14:15], 0
	v_mov_b64_e32 v[16:17], 0
	v_mov_b64_e32 v[22:23], 0
	v_mov_b64_e32 v[24:25], 0
	v_mov_b64_e32 v[30:31], 0
	v_mov_b64_e32 v[32:33], 0
	v_mov_b64_e32 v[38:39], 0
	v_mov_b64_e32 v[40:41], 0
	v_mov_b64_e32 v[46:47], 0
	v_mov_b64_e32 v[48:49], 0
	v_mov_b64_e32 v[54:55], 0
	v_mov_b64_e32 v[56:57], 0
	v_mov_b64_e32 v[10:11], 0
	v_mov_b64_e32 v[12:13], 0
	v_mov_b64_e32 v[18:19], 0
	v_mov_b64_e32 v[20:21], 0
	v_mov_b64_e32 v[26:27], 0
	v_mov_b64_e32 v[28:29], 0
	v_mov_b64_e32 v[34:35], 0
	v_mov_b64_e32 v[36:37], 0
	v_mov_b64_e32 v[42:43], 0
	v_mov_b64_e32 v[44:45], 0
	v_mov_b64_e32 v[50:51], 0
	v_mov_b64_e32 v[52:53], 0
	v_mov_b64_e32 v[58:59], 0
	v_mov_b64_e32 v[60:61], 0
	v_mov_b64_e32 v[62:63], 0
	v_mov_b64_e32 v[64:65], 0
	v_mov_b64_e32 v[66:67], 0
	v_mov_b64_e32 v[68:69], 0
	v_mov_b64_e32 v[70:71], 0
	v_mov_b64_e32 v[72:73], 0
	v_mov_b64_e32 v[78:79], 0
	v_mov_b64_e32 v[80:81], 0
	v_mov_b64_e32 v[86:87], 0
	v_mov_b64_e32 v[88:89], 0
	v_mov_b64_e32 v[94:95], 0
	v_mov_b64_e32 v[96:97], 0
	v_mov_b64_e32 v[102:103], 0
	v_mov_b64_e32 v[104:105], 0
	v_mov_b64_e32 v[110:111], 0
	v_mov_b64_e32 v[112:113], 0
	v_mov_b64_e32 v[118:119], 0
	v_mov_b64_e32 v[120:121], 0
	v_mov_b64_e32 v[74:75], 0
	v_mov_b64_e32 v[76:77], 0
	v_mov_b64_e32 v[82:83], 0
	v_mov_b64_e32 v[84:85], 0
	v_mov_b64_e32 v[90:91], 0
	v_mov_b64_e32 v[92:93], 0
	v_mov_b64_e32 v[98:99], 0
	v_mov_b64_e32 v[100:101], 0
	v_mov_b64_e32 v[106:107], 0
	v_mov_b64_e32 v[108:109], 0
	v_mov_b64_e32 v[114:115], 0
	v_mov_b64_e32 v[116:117], 0
	v_mov_b64_e32 v[122:123], 0
	v_mov_b64_e32 v[124:125], 0
	v_mov_b64_e32 v[126:127], 0
	v_mov_b64_e32 v[128:129], 0

; template <class Epi, class Sched, bool ALIGN_EPI = false, bool SP2 = false>
; __device__ __forceinline__ void gemm_phase(PG8_LAS unsigned char* lds, const Gemm g, const Sched& S, const Epi& E) {
;     ...
;         const bool has_next = S.next(ui + 1, nxt);
;         const char* nA = has_next ? (const char*)g.A + (size_t)nxt.pm * tstep + (size_t)nxt.k0 * 2 : cA; const char* nB = has_next ? (const char*)g.Bt + (size_t)nxt.pn * tstep + (size_t)nxt.k0 * 2 : cB;
;         const int nt = cur.nt;
;         for (int t = 0; t < nt; t += 2) {
;     ...
;         for (int a = 0; a < 2; ++a)
; #pragma unroll
;             for (int b = 0; b < 2; ++b)
; #pragma unroll
;                 for (int m = 0; m < 4; ++m)
; #pragma unroll
;                     for (int n = 0; n < 2; ++n) acc[a][b][m][n] = (f32x4){0.f, 0.f, 0.f, 0.f};
.LBB0_1217:
	s_ashr_i32 s27, s26, 31
	s_lshl_b64 s[28:29], s[26:27], 20
	s_add_u32 s28, s3, s28
	s_addc_u32 s29, s33, s29
	s_and_b64 s[30:31], s[4:5], exec
	s_cselect_b32 s27, s29, s47
	s_cselect_b32 s62, s28, s46
	s_ashr_i32 s25, s24, 31
	s_lshl_b64 s[30:31], s[24:25], 20
	s_add_u32 s30, s8, s30
	s_addc_u32 s31, s9, s31
	s_and_b64 s[50:51], s[4:5], exec
	s_cselect_b32 s25, s31, s49
	s_cselect_b32 s63, s30, s48
	s_add_u32 s46, s46, 0x80080
	s_addc_u32 s47, s47, 0
	s_add_u32 s64, s48, 0x100
	v_mov_b32_e32 v2, 0
	s_addc_u32 s65, s49, 0
	s_mov_b32 s66, -2
	v_mov_b32_e32 v3, v2
	v_mov_b64_e32 v[4:5], 0
	v_mov_b64_e32 v[10:11], 0
	v_mov_b64_e32 v[12:13], 0
	v_mov_b64_e32 v[18:19], 0
	v_mov_b64_e32 v[20:21], 0
	v_mov_b64_e32 v[26:27], 0
	v_mov_b64_e32 v[28:29], 0
	v_mov_b64_e32 v[34:35], 0
	v_mov_b64_e32 v[36:37], 0
	v_mov_b64_e32 v[42:43], 0
	v_mov_b64_e32 v[44:45], 0
	v_mov_b64_e32 v[50:51], 0
	v_mov_b64_e32 v[52:53], 0
	v_mov_b64_e32 v[58:59], 0
	v_mov_b64_e32 v[60:61], 0
	v_mov_b64_e32 v[6:7], 0
	v_mov_b64_e32 v[8:9], 0
	v_mov_b64_e32 v[14:15], 0
	v_mov_b64_e32 v[16:17], 0
	v_mov_b64_e32 v[22:23], 0
	v_mov_b64_e32 v[24:25], 0
	v_mov_b64_e32 v[30:31], 0
	v_mov_b64_e32 v[32:33], 0
	v_mov_b64_e32 v[38:39], 0
	v_mov_b64_e32 v[40:41], 0
	v_mov_b64_e32 v[46:47], 0
	v_mov_b64_e32 v[48:49], 0
	v_mov_b64_e32 v[54:55], 0
	v_mov_b64_e32 v[56:57], 0
	v_mov_b64_e32 v[62:63], 0
	v_mov_b64_e32 v[64:65], 0
	v_mov_b64_e32 v[66:67], 0
	v_mov_b64_e32 v[68:69], 0
	v_mov_b64_e32 v[74:75], 0
	v_mov_b64_e32 v[76:77], 0
	v_mov_b64_e32 v[82:83], 0
	v_mov_b64_e32 v[84:85], 0
	v_mov_b64_e32 v[90:91], 0
	v_mov_b64_e32 v[92:93], 0
	v_mov_b64_e32 v[98:99], 0
	v_mov_b64_e32 v[100:101], 0
	v_mov_b64_e32 v[106:107], 0
	v_mov_b64_e32 v[108:109], 0
	v_mov_b64_e32 v[114:115], 0
	v_mov_b64_e32 v[116:117], 0
	v_mov_b64_e32 v[122:123], 0
	v_mov_b64_e32 v[124:125], 0
	v_mov_b64_e32 v[70:71], 0
	v_mov_b64_e32 v[72:73], 0
	v_mov_b64_e32 v[78:79], 0
	v_mov_b64_e32 v[80:81], 0
	v_mov_b64_e32 v[86:87], 0
	v_mov_b64_e32 v[88:89], 0
	v_mov_b64_e32 v[94:95], 0
	v_mov_b64_e32 v[96:97], 0
	v_mov_b64_e32 v[102:103], 0
	v_mov_b64_e32 v[104:105], 0
	v_mov_b64_e32 v[110:111], 0
	v_mov_b64_e32 v[112:113], 0
	v_mov_b64_e32 v[118:119], 0
	v_mov_b64_e32 v[120:121], 0
	v_mov_b64_e32 v[126:127], 0
	v_mov_b64_e32 v[128:129], 0
